# deferred weight conversion (17408 layer-2/3 tiles converted in attention slack of layers 0/2), prep split 40/4 tiles per converter/S5 wave
# speedup vs baseline: 1.0117x; 1.0117x over previous
; __global__ void __launch_bounds__(NTHR) hybrid_encoder_fwd(Params P) {
;     ...
;             constexpr int PB_PAIR = (T_PAIR - T_W1 - T_W2) / 4, NBATCH = 2 * PB_PAIR, NB1 = 11712;
;     ...
;             if (bid >= 128) for (int bt = (bid - 128) * 8 + wid; bt < NB1; bt += (G - 128) * 8) {
; #pragma unroll 1
;                 for (int q = 0; q < 4; ++q) conv_dispatch(P, PREP_TILE(bt) + q, lane); }
;             for (int bt = NB1 + bid * 8 + wid; bt < NBATCH; bt += G * 8) {
; #pragma unroll 1
;                 for (int q = 0; q < 4; ++q) conv_dispatch(P, PREP_TILE(bt) + q, lane); }
.LBB0_10:
	s_cmpk_gt_i32 s2, 0x7f
	s_cselect_b64 s[4:5], -1, 0
	v_writelane_b32 v253, s4, 14
	s_and_b64 vcc, exec, s[4:5]
	s_mov_b64 s[0:1], -1
	v_writelane_b32 v253, s5, 15
	s_mov_b32 s4, s22
	v_writelane_b32 v253, s4, 16
	s_nop 1
	v_writelane_b32 v253, s5, 17
	s_cbranch_vccz .LBB0_55
	s_add_i32 s3, s22, 0xfffffc00
	s_mov_b32 s25, 60
	s_mov_b32 s39, 12
	s_mov_b32 vcc_lo, 0x400
	s_mov_b32 vcc_hi, -1
.Lcv_entry:
	s_waitcnt lgkmcnt(0)
	v_writelane_b32 v255, s86, 48
	v_writelane_b32 v255, s87, 49
	v_writelane_b32 v255, s88, 50
	v_writelane_b32 v255, s89, 51
	v_writelane_b32 v255, s12, 52
	v_writelane_b32 v255, s13, 53
	v_writelane_b32 v255, s14, 54
	v_writelane_b32 v255, s15, 55
	v_writelane_b32 v255, s16, 56
	v_writelane_b32 v255, s17, 57
	v_writelane_b32 v255, s18, 58
	v_writelane_b32 v255, s19, 59
	v_and_b32_e32 v2, 7, v201
	v_lshrrev_b32_e32 v3, 3, v201
	v_lshlrev_b32_e32 v4, 4, v2
	v_lshlrev_b32_e32 v5, 4, v3
	v_lshlrev_b32_e32 v7, 5, v2
	s_mov_b32 s30, 0
	s_min_u32 s0, s30, s25
	s_mul_i32 s0, s0, vcc_lo
	s_add_i32 s0, s0, s3
	s_min_u32 s0, s0, vcc_hi
	s_add_i32 s30, s30, 1
	s_cmp_ge_u32 s0, 0x7a00
	s_cselect_b32 s33, 1, 0
	s_mul_i32 s1, s33, 0x7a00
	s_sub_i32 s20, s0, s1
	s_cmp_lt_u32 s20, 0x1000
	s_cbranch_scc1 .Lcv0_win
	s_cmp_lt_u32 s20, 0x1800
	s_cbranch_scc1 .Lcv0_wout
	s_cmp_lt_u32 s20, 0x1a00
	s_cbranch_scc1 .Lcv0_glu
	s_cmp_lt_u32 s20, 0x3a00
	s_cbranch_scc1 .Lcv0_w1
	s_cmp_lt_u32 s20, 0x5a00
	s_cbranch_scc1 .Lcv0_w2
	s_cmp_lt_u32 s20, 0x7200
	s_cbranch_scc1 .Lcv0_qkv

; __device__ __forceinline__ unsigned cvt_pk_bf16(float lo, float hi) { unsigned r; asm volatile("v_cvt_pk_bf16_f32 %0, %1, %2" : "=v"(r) : "v"(lo), "v"(hi)); return r; }
; __device__ __forceinline__ void s5_gen(LAS unsigned char* lds, const Params& P, int j, int g) {
;     ...
;     for (int ch = tid; ch < 256 * 64; ch += NTHR) {
;         const int row = ch >> 6, kc = (ch & 63) * 8, dir = row >> 7, im = (row >> 6) & 1, pp = row & 63, t = kc >> 4, c0 = kc & 15; const int ex = (dir == 0) ? (31 - t) : t;
;         const f32x2 w = pw[(dir * 33 + ex) * 64 + pp]; float v[8];
; #pragma unroll
;         for (int e = 0; e < 8; ++e) { const f32x2 b = bb[(dir * 64 + pp) * 16 + c0 + e]; v[e] = im ? (w.x * b.y + w.y * b.x) : (w.x * b.x - w.y * b.y); }
;         u32x4 wv; wv.x = cvt_pk_bf16(v[0], v[1]); wv.y = cvt_pk_bf16(v[2], v[3]); wv.z = cvt_pk_bf16(v[4], v[5]); wv.w = cvt_pk_bf16(v[6], v[7]);
;         *(u32x4*)(B1 + (size_t)row * 512 + kc) = wv;
;     }
; __global__ void __launch_bounds__(NTHR) hybrid_encoder_fwd(Params P) {
;     ...
;         for (int it = bid; it < 128; it += G) { s5_gen(lds, P, it >> 6, it & 63);
;         }
;         {
;             constexpr int PB_PAIR = (T_PAIR - T_W1 - T_W2) / 4, NBATCH = 2 * PB_PAIR, NB1 = 11712;
;     ...
;             if (bid >= 128) for (int bt = (bid - 128) * 8 + wid; bt < NB1; bt += (G - 128) * 8) {
; #pragma unroll 1
;                 for (int q = 0; q < 4; ++q) conv_dispatch(P, PREP_TILE(bt) + q, lane); }
;             for (int bt = NB1 + bid * 8 + wid; bt < NBATCH; bt += G * 8) {
; #pragma unroll 1
;                 for (int q = 0; q < 4; ++q) conv_dispatch(P, PREP_TILE(bt) + q, lane); }
.LBB0_116:
	s_movk_i32 s6, 0x2000
	v_lshrrev_b32_e32 v7, 13, v6
	v_and_b32_e32 v8, 63, v4
	v_and_b32_e32 v9, 8, v5
	v_cmp_gt_u32_e32 vcc, s6, v6
	v_and_b32_e32 v12, 0x2000, v6
	v_mul_u32_u24_e32 v7, 33, v7
	v_cndmask_b32_e32 v11, v66, v67, vcc
	v_lshlrev_b32_e32 v14, 3, v8
	v_add_u32_e32 v12, 0, v12
	v_lshlrev_b32_e32 v8, 7, v8
	v_lshlrev_b32_e32 v9, 3, v9
	v_add_u32_e32 v13, 0x200, v6
	s_movk_i32 s6, 0x3dff
	v_add_lshl_u32 v7, v11, v7, 9
	v_add3_u32 v11, v12, v8, v9
	v_and_b32_e32 v86, 0x1000, v6
	v_cmp_lt_u32_e32 vcc, s6, v6
	v_mov_b32_e32 v6, v13
	v_add3_u32 v7, 0, v7, v14
	ds_read_b128 v[12:15], v11 offset:33808
	ds_read_b128 v[16:19], v11 offset:33824
	ds_read_b128 v[20:23], v11 offset:33840
	ds_read_b64 v[8:9], v7
	ds_read_b128 v[24:27], v11 offset:33792
	s_or_b64 s[0:1], vcc, s[0:1]
	v_cmp_eq_u32_e32 vcc, 0, v86
	s_mov_b64 s[6:7], 0x2000
	s_waitcnt lgkmcnt(1)
	v_pk_mul_f32 v[32:33], v[8:9], v[12:13] op_sel:[0,1] op_sel_hi:[1,0]
	v_pk_mul_f32 v[12:13], v[8:9], v[12:13]
	v_pk_mul_f32 v[34:35], v[8:9], v[14:15] op_sel:[0,1] op_sel_hi:[1,0]
	v_pk_mul_f32 v[14:15], v[8:9], v[14:15]
	v_pk_mul_f32 v[56:57], v[8:9], v[16:17] op_sel:[0,1] op_sel_hi:[1,0]
	v_pk_mul_f32 v[16:17], v[8:9], v[16:17]
	v_pk_mul_f32 v[58:59], v[8:9], v[18:19] op_sel:[0,1] op_sel_hi:[1,0]
	v_pk_mul_f32 v[18:19], v[8:9], v[18:19]
	s_waitcnt lgkmcnt(0)
	v_pk_mul_f32 v[28:29], v[8:9], v[24:25] op_sel:[0,1] op_sel_hi:[1,0]
	v_pk_mul_f32 v[24:25], v[8:9], v[24:25]
	v_pk_mul_f32 v[30:31], v[8:9], v[26:27] op_sel:[0,1] op_sel_hi:[1,0]
	v_pk_mul_f32 v[26:27], v[8:9], v[26:27]
	v_pk_mul_f32 v[60:61], v[8:9], v[20:21] op_sel:[0,1] op_sel_hi:[1,0]
	v_pk_mul_f32 v[20:21], v[8:9], v[20:21]
	v_pk_mul_f32 v[84:85], v[8:9], v[22:23] op_sel:[0,1] op_sel_hi:[1,0]
	v_pk_mul_f32 v[8:9], v[8:9], v[22:23]
	v_sub_f32_e32 v12, v12, v13
	v_add_f32_e32 v13, v34, v35
	v_sub_f32_e32 v14, v14, v15
	v_add_f32_e32 v15, v56, v57
	v_sub_f32_e32 v16, v16, v17
	v_add_f32_e32 v17, v58, v59
	v_sub_f32_e32 v18, v18, v19
	v_add_f32_e32 v7, v28, v29
	v_sub_f32_e32 v11, v24, v25
	v_add_f32_e32 v22, v30, v31
	v_sub_f32_e32 v23, v26, v27
	v_add_f32_e32 v24, v32, v33
	v_add_f32_e32 v19, v60, v61
	v_sub_f32_e32 v20, v20, v21
	v_add_f32_e32 v21, v84, v85
	v_sub_f32_e32 v8, v8, v9
	v_cndmask_b32_e32 v13, v13, v14, vcc
	v_cndmask_b32_e32 v14, v15, v16, vcc
	v_cndmask_b32_e32 v15, v17, v18, vcc
	v_add_u32_e32 v5, 0x1000, v5
	v_add_u32_e32 v4, 8, v4
	v_cndmask_b32_e32 v7, v7, v11, vcc
	v_cndmask_b32_e32 v9, v22, v23, vcc
	v_cndmask_b32_e32 v11, v24, v12, vcc
	v_cndmask_b32_e32 v16, v19, v20, vcc
	v_cndmask_b32_e32 v8, v21, v8, vcc
	v_cvt_pk_bf16_f32 v12, v7, v9
	v_cvt_pk_bf16_f32 v13, v11, v13
	v_cvt_pk_bf16_f32 v14, v14, v15
	v_cvt_pk_bf16_f32 v15, v16, v8
	global_store_dwordx4 v[2:3], v[12:15], off
	v_lshl_add_u64 v[2:3], v[2:3], 0, s[6:7]
	s_andn2_b64 exec, exec, s[0:1]
	s_cbranch_execnz .LBB0_116
	s_or_b64 exec, exec, s[0:1]
	s_add_i32 s29, s29, s94
	s_add_i32 s28, s28, s94
	s_cmpk_gt_i32 s29, 0x7f
	s_barrier
	s_cbranch_scc0 .LBB0_57
	v_readlane_b32 s22, v253, 16
	v_readlane_b32 s23, v253, 17
	s_add_i32 s3, s22, 0xa000
	s_mov_b32 s25, 3
	s_mov_b32 s39, 0
	s_mov_b32 vcc_lo, 0x400
	s_mov_b32 vcc_hi, -1
	s_branch .Lcv_entry

; __global__ void __launch_bounds__(NTHR) hybrid_encoder_fwd(Params P) {
;     ...
;                     attn_a_phase(lds, bid - 64, 192, 8, Qb, Kb, Vb, P.in[1], NUM, ML);
.LBB0_572:
	v_writelane_b32 v150, s0, 0
	v_writelane_b32 v150, s1, 1
	v_writelane_b32 v150, s3, 2
	v_writelane_b32 v150, s4, 3
	v_writelane_b32 v150, s5, 4
	v_writelane_b32 v150, s6, 5
	v_writelane_b32 v150, s7, 6
	v_writelane_b32 v150, s8, 7
	v_writelane_b32 v150, s9, 8
	v_writelane_b32 v150, s10, 9
	v_writelane_b32 v150, s11, 10
	v_writelane_b32 v150, s12, 11
	v_writelane_b32 v150, s13, 12
	v_writelane_b32 v150, s14, 13
	v_writelane_b32 v150, s15, 14
	v_writelane_b32 v150, s16, 15
	v_writelane_b32 v150, s17, 16
	v_writelane_b32 v150, s18, 17
	v_writelane_b32 v150, s19, 18
	v_writelane_b32 v150, s20, 19
	v_writelane_b32 v150, s21, 20
	v_writelane_b32 v150, s22, 21
	v_writelane_b32 v150, s23, 22
	v_writelane_b32 v150, s24, 23
	v_writelane_b32 v150, s25, 24
	v_writelane_b32 v150, s30, 25
	v_writelane_b32 v150, s33, 26
	v_writelane_b32 v150, s38, 27
	v_writelane_b32 v150, s39, 28
	v_writelane_b32 v150, s72, 29
	v_writelane_b32 v150, s73, 30
	v_writelane_b32 v150, s74, 31
	v_writelane_b32 v150, s75, 32
	v_writelane_b32 v150, s76, 33
	v_writelane_b32 v150, s77, 34
	v_writelane_b32 v150, s78, 35
	v_writelane_b32 v150, s79, 36
	v_writelane_b32 v150, s80, 37
	v_writelane_b32 v150, s81, 38
	v_writelane_b32 v150, s82, 39
	v_writelane_b32 v150, s83, 40
	v_writelane_b32 v150, s86, 41
	v_writelane_b32 v150, s87, 42
	v_writelane_b32 v150, s88, 43
	v_writelane_b32 v150, s89, 44
	v_writelane_b32 v150, vcc_lo, 45
	v_writelane_b32 v150, vcc_hi, 46
	v_readlane_b32 s0, v252, 25
	v_readfirstlane_b32 s1, v200
	s_lshr_b32 s1, s1, 6
	s_sub_i32 s3, s2, 64
	s_lshl_b32 s3, s3, 3
	s_add_i32 s3, s3, s1
	s_mov_b32 s20, 0xb000
	s_mov_b32 s21, 0xd400
	s_mov_b32 s22, 0xd3ff
	s_mov_b32 s23, 0xf3ff
	s_cmp_eq_u32 s0, 0
	s_cselect_b32 s20, s20, s21
	s_cselect_b32 vcc_hi, s22, s23
	s_add_i32 s3, s3, s20
	s_mov_b32 vcc_lo, 0x600
	s_mov_b32 s25, 5
	s_mov_b32 s39, 1
	v_readlane_b32 s86, v255, 48
	v_readlane_b32 s87, v255, 49
	v_readlane_b32 s88, v255, 50
	v_readlane_b32 s89, v255, 51
	v_readlane_b32 s12, v255, 52
	v_readlane_b32 s13, v255, 53
	v_readlane_b32 s14, v255, 54
	v_readlane_b32 s15, v255, 55
	v_readlane_b32 s16, v255, 56
	v_readlane_b32 s17, v255, 57
	v_readlane_b32 s18, v255, 58
	v_readlane_b32 s19, v255, 59

; __global__ void __launch_bounds__(NTHR) hybrid_encoder_fwd(Params P) {
;     ...
;                     attn_a_phase(lds, bid - 64, 192, 8, Qb, Kb, Vb, P.in[1], NUM, ML);
.Lcw_exit:
	v_readlane_b32 s0, v150, 0
	v_readlane_b32 s1, v150, 1
	v_readlane_b32 s3, v150, 2
	v_readlane_b32 s4, v150, 3
	v_readlane_b32 s5, v150, 4
	v_readlane_b32 s6, v150, 5
	v_readlane_b32 s7, v150, 6
	v_readlane_b32 s8, v150, 7
	v_readlane_b32 s9, v150, 8
	v_readlane_b32 s10, v150, 9
	v_readlane_b32 s11, v150, 10
	v_readlane_b32 s12, v150, 11
	v_readlane_b32 s13, v150, 12
	v_readlane_b32 s14, v150, 13
	v_readlane_b32 s15, v150, 14
	v_readlane_b32 s16, v150, 15
	v_readlane_b32 s17, v150, 16
	v_readlane_b32 s18, v150, 17
	v_readlane_b32 s19, v150, 18
	v_readlane_b32 s20, v150, 19
	v_readlane_b32 s21, v150, 20
	v_readlane_b32 s22, v150, 21
	v_readlane_b32 s23, v150, 22
	v_readlane_b32 s24, v150, 23
	v_readlane_b32 s25, v150, 24
	v_readlane_b32 s30, v150, 25
	v_readlane_b32 s33, v150, 26
	v_readlane_b32 s38, v150, 27
	v_readlane_b32 s39, v150, 28
	v_readlane_b32 s72, v150, 29
	v_readlane_b32 s73, v150, 30
	v_readlane_b32 s74, v150, 31
	v_readlane_b32 s75, v150, 32
	v_readlane_b32 s76, v150, 33
	v_readlane_b32 s77, v150, 34
	v_readlane_b32 s78, v150, 35
	v_readlane_b32 s79, v150, 36
	v_readlane_b32 s80, v150, 37
	v_readlane_b32 s81, v150, 38
	v_readlane_b32 s82, v150, 39
	v_readlane_b32 s83, v150, 40
	v_readlane_b32 s86, v150, 41
	v_readlane_b32 s87, v150, 42
	v_readlane_b32 s88, v150, 43
	v_readlane_b32 s89, v150, 44
	v_readlane_b32 vcc_lo, v150, 45
	v_readlane_b32 vcc_hi, v150, 46
	s_nop 3
	s_mov_b64 s[0:1], 0
